# stack: P2 unit-1 tile exchange + attention loop vmcnt ladder made last-iteration-only + attention epilogue gate loads prefetched (8 up front, no per-step waits)
# speedup vs baseline: 1.0134x; 1.0037x over previous
.LBB0_507:
	s_or_b64 exec, exec, s[6:7]
	v_add_u32_e32 v74, s29, v195
	s_waitcnt vmcnt(0) lgkmcnt(0)
	s_waitcnt lgkmcnt(0)
	s_barrier
	ds_read_b128 v[66:69], v74
	ds_read_b128 v[70:73], v74 offset:32
	s_add_u32 s6, s52, s70
	s_addc_u32 s7, s53, s71
	s_lshl_b64 s[98:99], s[10:11], 12
	s_add_u32 s98, s6, s98
	s_addc_u32 s99, s7, s99
	s_mov_b64 s[100:101], 0x4000
	v_lshl_add_u64 v[116:117], s[98:99], 0, v[178:179]
	v_lshlrev_b32_e32 v118, 1, v180
	v_mov_b32_e32 v119, v179
	v_lshl_add_u64 v[116:117], v[116:117], 0, v[118:119]
	global_load_dwordx4 v[84:87], v[116:117], off
	v_lshl_add_u64 v[116:117], v[116:117], 0, s[100:101]
	global_load_dwordx4 v[88:91], v[116:117], off
	v_lshl_add_u64 v[116:117], v[116:117], 0, s[100:101]
	global_load_dwordx4 v[92:95], v[116:117], off
	v_lshl_add_u64 v[116:117], v[116:117], 0, s[100:101]
	global_load_dwordx4 v[96:99], v[116:117], off
	v_lshl_add_u64 v[116:117], v[116:117], 0, s[100:101]
	global_load_dwordx4 v[100:103], v[116:117], off
	v_lshl_add_u64 v[116:117], v[116:117], 0, s[100:101]
	global_load_dwordx4 v[104:107], v[116:117], off
	v_lshl_add_u64 v[116:117], v[116:117], 0, s[100:101]
	global_load_dwordx4 v[108:111], v[116:117], off
	v_lshl_add_u64 v[116:117], v[116:117], 0, s[100:101]
	global_load_dwordx4 v[112:115], v[116:117], off
	s_lshl_b32 s28, s28, 13
	s_waitcnt lgkmcnt(1)
	v_rcp_f32_e32 v75, v66
	s_add_i32 s28, s28, 0
	v_rcp_f32_e32 v76, v67
	v_rcp_f32_e32 v77, v68
	v_mul_f32_e32 v2, v2, v75
	v_rcp_f32_e32 v78, v69
	s_waitcnt lgkmcnt(0)
	v_rcp_f32_e32 v79, v70
	ds_read_b128 v[66:69], v74 offset:64
	v_rcp_f32_e32 v80, v71
	v_rcp_f32_e32 v81, v72
	v_rcp_f32_e32 v82, v73
	ds_read_b128 v[70:73], v74 offset:96
	v_add3_u32 v74, s28, v197, v198
	v_cvt_pk_bf16_f32 v2, v2, v2
	ds_write_b16 v74, v2
	v_mul_f32_e32 v2, v50, v75
	v_cvt_pk_bf16_f32 v2, v2, v2
	ds_write_b16 v74, v2 offset:64
	v_mul_f32_e32 v2, v34, v75
	v_cvt_pk_bf16_f32 v2, v2, v2
	ds_write_b16 v74, v2 offset:128
	v_mul_f32_e32 v2, v18, v75
	v_cvt_pk_bf16_f32 v2, v2, v2
	ds_write_b16 v74, v2 offset:192
	v_mul_f32_e32 v2, v3, v76
	v_cvt_pk_bf16_f32 v2, v2, v2
	ds_write_b16 v74, v2 offset:256
	v_mul_f32_e32 v2, v51, v76
	v_cvt_pk_bf16_f32 v2, v2, v2
	ds_write_b16 v74, v2 offset:320
	v_mul_f32_e32 v2, v35, v76
	v_cvt_pk_bf16_f32 v2, v2, v2
	ds_write_b16 v74, v2 offset:384
	v_mul_f32_e32 v2, v19, v76
	v_cvt_pk_bf16_f32 v2, v2, v2
	ds_write_b16 v74, v2 offset:448
	v_mul_f32_e32 v2, v4, v77
	v_cvt_pk_bf16_f32 v2, v2, v2
	ds_write_b16 v74, v2 offset:512
	v_mul_f32_e32 v2, v52, v77
	v_cvt_pk_bf16_f32 v2, v2, v2
	ds_write_b16 v74, v2 offset:576
	v_mul_f32_e32 v2, v36, v77
	v_cvt_pk_bf16_f32 v2, v2, v2
	ds_write_b16 v74, v2 offset:640
	v_mul_f32_e32 v2, v20, v77
	v_cvt_pk_bf16_f32 v2, v2, v2
	ds_write_b16 v74, v2 offset:704
	v_mul_f32_e32 v2, v5, v78
	v_cvt_pk_bf16_f32 v2, v2, v2
	ds_write_b16 v74, v2 offset:768
	v_mul_f32_e32 v2, v53, v78
	v_cvt_pk_bf16_f32 v2, v2, v2
	ds_write_b16 v74, v2 offset:832
	v_mul_f32_e32 v2, v37, v78
	v_cvt_pk_bf16_f32 v2, v2, v2
	ds_write_b16 v74, v2 offset:896
	v_mul_f32_e32 v2, v21, v78
	v_cvt_pk_bf16_f32 v2, v2, v2
	ds_write_b16 v74, v2 offset:960
	v_mul_f32_e32 v2, v6, v79
	v_cvt_pk_bf16_f32 v2, v2, v2
	ds_write_b16 v74, v2 offset:2048
	v_mul_f32_e32 v2, v54, v79
	v_cvt_pk_bf16_f32 v2, v2, v2
	ds_write_b16 v74, v2 offset:2112
	v_mul_f32_e32 v2, v38, v79
	v_cvt_pk_bf16_f32 v2, v2, v2
	ds_write_b16 v74, v2 offset:2176
	v_mul_f32_e32 v2, v22, v79
	v_cvt_pk_bf16_f32 v2, v2, v2
	ds_write_b16 v74, v2 offset:2240
	v_mul_f32_e32 v2, v7, v80
	v_cvt_pk_bf16_f32 v2, v2, v2
	ds_write_b16 v74, v2 offset:2304
	v_mul_f32_e32 v2, v55, v80
	v_cvt_pk_bf16_f32 v2, v2, v2
	ds_write_b16 v74, v2 offset:2368
	v_mul_f32_e32 v2, v39, v80
	v_cvt_pk_bf16_f32 v2, v2, v2
	ds_write_b16 v74, v2 offset:2432
	v_mul_f32_e32 v2, v23, v80
	v_cvt_pk_bf16_f32 v2, v2, v2
	ds_write_b16 v74, v2 offset:2496
	v_mul_f32_e32 v2, v8, v81
	v_cvt_pk_bf16_f32 v2, v2, v2
	ds_write_b16 v74, v2 offset:2560
	v_mul_f32_e32 v2, v56, v81
	v_cvt_pk_bf16_f32 v2, v2, v2
	ds_write_b16 v74, v2 offset:2624
	v_mul_f32_e32 v2, v40, v81
	v_cvt_pk_bf16_f32 v2, v2, v2
	ds_write_b16 v74, v2 offset:2688
	v_mul_f32_e32 v2, v24, v81
	v_cvt_pk_bf16_f32 v2, v2, v2
	ds_write_b16 v74, v2 offset:2752
	v_mul_f32_e32 v2, v9, v82
	v_cvt_pk_bf16_f32 v2, v2, v2
	ds_write_b16 v74, v2 offset:2816
	v_mul_f32_e32 v2, v57, v82
	v_cvt_pk_bf16_f32 v2, v2, v2
	s_waitcnt lgkmcnt(14)
	v_rcp_f32_e32 v66, v66
	ds_write_b16 v74, v2 offset:2880
	v_mul_f32_e32 v2, v41, v82
	v_cvt_pk_bf16_f32 v2, v2, v2
	ds_write_b16 v74, v2 offset:2944
	v_mul_f32_e32 v2, v25, v82
	v_cvt_pk_bf16_f32 v2, v2, v2
	ds_write_b16 v74, v2 offset:3008
	v_mul_f32_e32 v2, v10, v66
	v_cvt_pk_bf16_f32 v2, v2, v2
	ds_write_b16 v74, v2 offset:4096
	v_mul_f32_e32 v2, v58, v66
	v_cvt_pk_bf16_f32 v2, v2, v2
	v_rcp_f32_e32 v67, v67
	ds_write_b16 v74, v2 offset:4160
	v_mul_f32_e32 v2, v42, v66
	v_cvt_pk_bf16_f32 v2, v2, v2
	ds_write_b16 v74, v2 offset:4224
	v_mul_f32_e32 v2, v26, v66
	v_cvt_pk_bf16_f32 v2, v2, v2
	ds_write_b16 v74, v2 offset:4288
	v_mul_f32_e32 v2, v11, v67
	v_cvt_pk_bf16_f32 v2, v2, v2
	ds_write_b16 v74, v2 offset:4352
	v_mul_f32_e32 v2, v59, v67
	v_cvt_pk_bf16_f32 v2, v2, v2
	v_rcp_f32_e32 v68, v68
	ds_write_b16 v74, v2 offset:4416
	v_mul_f32_e32 v2, v43, v67
	v_cvt_pk_bf16_f32 v2, v2, v2
	ds_write_b16 v74, v2 offset:4480
	v_mul_f32_e32 v2, v27, v67
	v_cvt_pk_bf16_f32 v2, v2, v2
	ds_write_b16 v74, v2 offset:4544
	v_mul_f32_e32 v2, v12, v68
	v_cvt_pk_bf16_f32 v2, v2, v2
	ds_write_b16 v74, v2 offset:4608
	v_mul_f32_e32 v2, v60, v68
	v_cvt_pk_bf16_f32 v2, v2, v2
	v_rcp_f32_e32 v69, v69
	ds_write_b16 v74, v2 offset:4672
	v_mul_f32_e32 v2, v44, v68
	v_cvt_pk_bf16_f32 v2, v2, v2
	ds_write_b16 v74, v2 offset:4736
	v_mul_f32_e32 v2, v28, v68
	v_cvt_pk_bf16_f32 v2, v2, v2
	ds_write_b16 v74, v2 offset:4800
	v_mul_f32_e32 v2, v13, v69
	v_cvt_pk_bf16_f32 v2, v2, v2
	ds_write_b16 v74, v2 offset:4864
	v_mul_f32_e32 v2, v61, v69
	v_cvt_pk_bf16_f32 v2, v2, v2
	v_rcp_f32_e32 v70, v70
	ds_write_b16 v74, v2 offset:4928
	v_mul_f32_e32 v2, v45, v69
	v_cvt_pk_bf16_f32 v2, v2, v2
	ds_write_b16 v74, v2 offset:4992
	v_mul_f32_e32 v2, v29, v69
	v_cvt_pk_bf16_f32 v2, v2, v2
	ds_write_b16 v74, v2 offset:5056
	v_mul_f32_e32 v2, v14, v70
	v_cvt_pk_bf16_f32 v2, v2, v2
	ds_write_b16 v74, v2 offset:6144
	v_mul_f32_e32 v2, v62, v70
	v_cvt_pk_bf16_f32 v2, v2, v2
	v_rcp_f32_e32 v71, v71
	ds_write_b16 v74, v2 offset:6208
	v_mul_f32_e32 v2, v46, v70
	v_cvt_pk_bf16_f32 v2, v2, v2
	ds_write_b16 v74, v2 offset:6272
	v_mul_f32_e32 v2, v30, v70
	v_cvt_pk_bf16_f32 v2, v2, v2
	ds_write_b16 v74, v2 offset:6336
	v_mul_f32_e32 v2, v15, v71
	v_cvt_pk_bf16_f32 v2, v2, v2
	ds_write_b16 v74, v2 offset:6400
	v_mul_f32_e32 v2, v63, v71
	v_cvt_pk_bf16_f32 v2, v2, v2
	v_rcp_f32_e32 v72, v72
	ds_write_b16 v74, v2 offset:6464
	v_mul_f32_e32 v2, v47, v71
	v_cvt_pk_bf16_f32 v2, v2, v2
	ds_write_b16 v74, v2 offset:6528
	v_mul_f32_e32 v2, v31, v71
	v_cvt_pk_bf16_f32 v2, v2, v2
	ds_write_b16 v74, v2 offset:6592
	v_mul_f32_e32 v2, v16, v72
	v_cvt_pk_bf16_f32 v2, v2, v2
	ds_write_b16 v74, v2 offset:6656
	v_mul_f32_e32 v2, v64, v72
	v_cvt_pk_bf16_f32 v2, v2, v2
	v_rcp_f32_e32 v73, v73
	ds_write_b16 v74, v2 offset:6720
	v_mul_f32_e32 v2, v48, v72
	v_cvt_pk_bf16_f32 v2, v2, v2
	ds_write_b16 v74, v2 offset:6784
	v_mul_f32_e32 v2, v32, v72
	v_cvt_pk_bf16_f32 v2, v2, v2
	ds_write_b16 v74, v2 offset:6848
	v_mul_f32_e32 v2, v17, v73
	v_cvt_pk_bf16_f32 v2, v2, v2
	ds_write_b16 v74, v2 offset:6912
	v_mul_f32_e32 v2, v65, v73
	v_cvt_pk_bf16_f32 v2, v2, v2
	ds_write_b16 v74, v2 offset:6976
	v_mul_f32_e32 v2, v49, v73
	v_cvt_pk_bf16_f32 v2, v2, v2
	s_lshl_b64 s[30:31], s[10:11], 12
	ds_write_b16 v74, v2 offset:7040
	v_mul_f32_e32 v2, v33, v73
	s_add_u32 s6, s6, s30
	v_cvt_pk_bf16_f32 v2, v2, v2
	s_addc_u32 s7, s7, s31
	ds_write_b16 v74, v2 offset:7104
	v_lshl_add_u64 v[2:3], s[6:7], 0, v[178:179]
	v_lshlrev_b32_e32 v4, 1, v180
	v_mov_b32_e32 v5, v179
	s_waitcnt lgkmcnt(0)
	v_lshl_add_u64 v[2:3], v[2:3], 0, v[4:5]
	s_nop 0
	v_add3_u32 v4, s28, v199, v200
	ds_read_b128 v[10:13], v4
	s_add_i32 s6, s10, s68
	s_mov_b64 s[36:37], 0
	s_waitcnt lgkmcnt(0)
	v_lshlrev_b32_e32 v14, 16, v10
	v_and_b32_e32 v10, 0xffff0000, v10
	s_waitcnt vmcnt(0)
	v_lshlrev_b32_e32 v5, 16, v84
	v_and_b32_e32 v6, 0xffff0000, v84
	v_mul_f32_e32 v5, v5, v14
	v_mul_f32_e32 v6, v6, v10
	v_cvt_pk_bf16_f32 v10, v5, v6
	v_lshlrev_b32_e32 v5, 16, v85
	v_lshlrev_b32_e32 v6, 16, v11
	v_mul_f32_e32 v5, v5, v6
	v_and_b32_e32 v6, 0xffff0000, v85
	v_and_b32_e32 v7, 0xffff0000, v11
	v_mul_f32_e32 v6, v6, v7
	v_cvt_pk_bf16_f32 v11, v5, v6
	v_lshlrev_b32_e32 v5, 16, v86
	v_lshlrev_b32_e32 v6, 16, v12
	v_mul_f32_e32 v5, v5, v6
	v_and_b32_e32 v6, 0xffff0000, v86
	v_and_b32_e32 v7, 0xffff0000, v12
	v_mul_f32_e32 v6, v6, v7
	v_cvt_pk_bf16_f32 v12, v5, v6
	v_lshlrev_b32_e32 v5, 16, v87
	v_lshlrev_b32_e32 v6, 16, v13
	v_mul_f32_e32 v5, v5, v6
	v_and_b32_e32 v6, 0xffff0000, v87
	v_and_b32_e32 v7, 0xffff0000, v13
	v_mul_f32_e32 v6, v6, v7
	v_cvt_pk_bf16_f32 v13, v5, v6
	v_add_co_u32_e32 v6, vcc, s14, v2
	v_or_b32_e32 v5, s25, v180
	s_nop 0
	v_addc_co_u32_e32 v7, vcc, 0, v3, vcc
	s_nop 0
	v_add_u32_e32 v6, s6, v1
	v_lshlrev_b32_e32 v18, 2, v6
	v_and_b32_e32 v22, 32, v18
	ds_read_b128 v[18:21], v4 offset:1024
	v_lshrrev_b32_e32 v5, 6, v5
	v_lshrrev_b32_e32 v7, 2, v6
	v_lshrrev_b32_e32 v8, 3, v6
	v_lshlrev_b32_e32 v9, 6, v6
	v_and_or_b32 v7, v7, s21, v5
	v_and_or_b32 v8, v8, 14, v201
	v_and_b32_e32 v9, 0x3c0, v9
	v_lshlrev_b32_e32 v7, 14, v7
	v_lshlrev_b32_e32 v8, 10, v8
	v_bitop3_b32 v9, v9, v22, v202 bitop3:0x36
	v_or3_b32 v7, v9, v8, v7
	global_store_dwordx4 v7, v[10:13], s[58:59]
	s_waitcnt lgkmcnt(0)
	v_lshlrev_b32_e32 v8, 16, v18
	v_and_b32_e32 v9, 0xffff0000, v18
	v_and_b32_e32 v10, 0xffff0000, v19
	v_and_b32_e32 v11, 0xffff0000, v20
	v_and_b32_e32 v12, 0xffff0000, v21
	s_nop 0
	v_lshlrev_b32_e32 v7, 16, v88
	v_mul_f32_e32 v7, v7, v8
	v_and_b32_e32 v8, 0xffff0000, v88
	v_mul_f32_e32 v8, v8, v9
	v_cvt_pk_bf16_f32 v8, v7, v8
	v_lshlrev_b32_e32 v7, 16, v89
	v_lshlrev_b32_e32 v9, 16, v19
	v_mul_f32_e32 v7, v7, v9
	v_and_b32_e32 v9, 0xffff0000, v89
	v_mul_f32_e32 v9, v9, v10
	v_cvt_pk_bf16_f32 v9, v7, v9
	v_lshlrev_b32_e32 v7, 16, v90
	v_lshlrev_b32_e32 v10, 16, v20
	v_mul_f32_e32 v7, v7, v10
	v_and_b32_e32 v10, 0xffff0000, v90
	v_mul_f32_e32 v10, v10, v11
	v_cvt_pk_bf16_f32 v10, v7, v10
	v_lshlrev_b32_e32 v7, 16, v91
	v_lshlrev_b32_e32 v11, 16, v21
	v_mul_f32_e32 v7, v7, v11
	v_and_b32_e32 v11, 0xffff0000, v91
	v_mul_f32_e32 v11, v11, v12
	v_add_co_u32_e32 v12, vcc, s1, v2
	v_cvt_pk_bf16_f32 v11, v7, v11
	v_add_u32_e32 v7, 4, v6
	s_nop 0
	v_addc_co_u32_e32 v13, vcc, 0, v3, vcc
	s_nop 0
	v_lshrrev_b32_e32 v16, 2, v7
	v_and_or_b32 v16, v16, s21, v5
	v_lshlrev_b32_e32 v20, 14, v16
	v_lshrrev_b32_e32 v16, 3, v7
	v_and_or_b32 v16, v16, 14, v201
	v_lshlrev_b32_e32 v17, 6, v7
	v_and_b32_e32 v21, 0x3c0, v17
	v_lshlrev_b32_e32 v22, 10, v16
	ds_read_b128 v[16:19], v4 offset:2048
	v_lshlrev_b32_e32 v7, 2, v7
	v_and_b32_e32 v7, 32, v7
	v_bitop3_b32 v7, v21, v7, v202 bitop3:0x36
	v_or3_b32 v7, v7, v22, v20
	global_store_dwordx4 v7, v[8:11], s[58:59]
	s_nop 0
	v_lshlrev_b32_e32 v7, 16, v92
	s_waitcnt lgkmcnt(0)
	v_lshlrev_b32_e32 v8, 16, v16
	v_mul_f32_e32 v7, v7, v8
	v_and_b32_e32 v8, 0xffff0000, v92
	v_and_b32_e32 v9, 0xffff0000, v16
	v_mul_f32_e32 v8, v8, v9
	v_cvt_pk_bf16_f32 v8, v7, v8
	v_lshlrev_b32_e32 v7, 16, v93
	v_lshlrev_b32_e32 v9, 16, v17
	v_mul_f32_e32 v7, v7, v9
	v_and_b32_e32 v9, 0xffff0000, v93
	v_and_b32_e32 v10, 0xffff0000, v17
	v_mul_f32_e32 v9, v9, v10
	v_cvt_pk_bf16_f32 v9, v7, v9
	v_lshlrev_b32_e32 v7, 16, v94
	v_lshlrev_b32_e32 v10, 16, v18
	v_mul_f32_e32 v7, v7, v10
	v_and_b32_e32 v10, 0xffff0000, v94
	v_and_b32_e32 v11, 0xffff0000, v18
	v_mul_f32_e32 v10, v10, v11
	v_cvt_pk_bf16_f32 v10, v7, v10
	v_lshlrev_b32_e32 v7, 16, v95
	v_lshlrev_b32_e32 v11, 16, v19
	v_mul_f32_e32 v7, v7, v11
	v_and_b32_e32 v11, 0xffff0000, v95
	v_and_b32_e32 v12, 0xffff0000, v19
	v_mul_f32_e32 v11, v11, v12
	v_add_co_u32_e32 v12, vcc, s2, v2
	v_cvt_pk_bf16_f32 v11, v7, v11
	v_add_u32_e32 v7, 8, v6
	s_nop 0
	v_addc_co_u32_e32 v13, vcc, 0, v3, vcc
	s_nop 0
	v_lshrrev_b32_e32 v16, 2, v7
	v_lshrrev_b32_e32 v17, 3, v7
	v_lshlrev_b32_e32 v18, 6, v7
	v_and_or_b32 v16, v16, s21, v5
	v_and_or_b32 v20, v17, 14, v201
	v_and_b32_e32 v21, 0x3c0, v18
	v_lshlrev_b32_e32 v22, 14, v16
	ds_read_b128 v[16:19], v4 offset:3072
	v_lshlrev_b32_e32 v7, 2, v7
	v_and_b32_e32 v7, 32, v7
	v_lshlrev_b32_e32 v20, 10, v20
	v_bitop3_b32 v7, v21, v7, v202 bitop3:0x36
	v_or3_b32 v7, v7, v20, v22
	global_store_dwordx4 v7, v[8:11], s[58:59]
	s_waitcnt lgkmcnt(0)
	v_lshlrev_b32_e32 v7, 16, v16
	s_nop 0
	v_lshlrev_b32_e32 v20, 16, v97
	v_and_b32_e32 v8, 0xffff0000, v16
	v_lshlrev_b32_e32 v9, 16, v17
	v_and_b32_e32 v10, 0xffff0000, v17
	v_lshlrev_b32_e32 v11, 16, v18
	v_and_b32_e32 v16, 0xffff0000, v18
	v_lshlrev_b32_e32 v17, 16, v19
	v_and_b32_e32 v18, 0xffff0000, v19
	v_lshlrev_b32_e32 v19, 16, v96
	v_and_b32_e32 v12, 0xffff0000, v96
	v_and_b32_e32 v13, 0xffff0000, v97
	v_lshlrev_b32_e32 v21, 16, v98
	v_and_b32_e32 v14, 0xffff0000, v98
	v_lshlrev_b32_e32 v22, 16, v99
	v_mul_f32_e32 v8, v12, v8
	v_mul_f32_e32 v9, v20, v9
	v_mul_f32_e32 v10, v13, v10
	v_mul_f32_e32 v12, v14, v16
	v_and_b32_e32 v15, 0xffff0000, v99
	v_mul_f32_e32 v7, v19, v7
	v_mul_f32_e32 v11, v21, v11
	v_mul_f32_e32 v13, v22, v17
	v_cvt_pk_bf16_f32 v8, v7, v8
	v_cvt_pk_bf16_f32 v9, v9, v10
	v_cvt_pk_bf16_f32 v10, v11, v12
	v_add_co_u32_e32 v12, vcc, s13, v2
	v_mul_f32_e32 v7, v15, v18
	v_cvt_pk_bf16_f32 v11, v13, v7
	s_nop 0
	v_addc_co_u32_e32 v13, vcc, 0, v3, vcc
	s_nop 0
	v_add_u32_e32 v7, 12, v6
	v_lshrrev_b32_e32 v16, 2, v7
	v_lshrrev_b32_e32 v17, 3, v7
	v_lshlrev_b32_e32 v18, 6, v7
	v_and_or_b32 v16, v16, s21, v5
	v_and_or_b32 v22, v17, 14, v201
	v_and_b32_e32 v23, 0x3c0, v18
	v_lshlrev_b32_e32 v24, 14, v16
	ds_read_b128 v[16:19], v4 offset:4096
	v_lshlrev_b32_e32 v7, 2, v7
	v_and_b32_e32 v7, 32, v7
	v_lshlrev_b32_e32 v22, 10, v22
	v_bitop3_b32 v7, v23, v7, v202 bitop3:0x36
	v_or3_b32 v7, v7, v22, v24
	v_add_co_u32_e32 v20, vcc, s3, v2
	global_store_dwordx4 v7, v[8:11], s[58:59]
	s_waitcnt lgkmcnt(0)
	v_lshlrev_b32_e32 v7, 16, v16
	v_addc_co_u32_e32 v21, vcc, 0, v3, vcc
	v_and_b32_e32 v8, 0xffff0000, v16
	v_lshlrev_b32_e32 v9, 16, v17
	v_and_b32_e32 v10, 0xffff0000, v17
	v_lshlrev_b32_e32 v11, 16, v18
	v_and_b32_e32 v16, 0xffff0000, v18
	v_lshlrev_b32_e32 v17, 16, v19
	v_and_b32_e32 v18, 0xffff0000, v19
	s_nop 0
	v_lshlrev_b32_e32 v19, 16, v100
	v_and_b32_e32 v12, 0xffff0000, v100
	v_lshlrev_b32_e32 v22, 16, v101
	v_and_b32_e32 v13, 0xffff0000, v101
	v_lshlrev_b32_e32 v23, 16, v102
	v_and_b32_e32 v14, 0xffff0000, v102
	v_lshlrev_b32_e32 v24, 16, v103
	v_and_b32_e32 v15, 0xffff0000, v103
	v_mul_f32_e32 v8, v12, v8
	v_mul_f32_e32 v9, v22, v9
	v_mul_f32_e32 v10, v13, v10
	v_mul_f32_e32 v11, v23, v11
	v_mul_f32_e32 v12, v14, v16
	v_mul_f32_e32 v13, v24, v17
	v_mul_f32_e32 v14, v15, v18
	v_mul_f32_e32 v7, v19, v7
	v_cvt_pk_bf16_f32 v8, v7, v8
	v_cvt_pk_bf16_f32 v9, v9, v10
	v_cvt_pk_bf16_f32 v10, v11, v12
	v_cvt_pk_bf16_f32 v11, v13, v14
	s_nop 0
	v_add_u32_e32 v7, 16, v6
	v_lshrrev_b32_e32 v16, 2, v7
	v_lshrrev_b32_e32 v17, 3, v7
	v_lshlrev_b32_e32 v18, 6, v7
	v_and_or_b32 v16, v16, s21, v5
	v_and_or_b32 v22, v17, 14, v201
	v_and_b32_e32 v23, 0x3c0, v18
	v_lshlrev_b32_e32 v24, 14, v16
	ds_read_b128 v[16:19], v4 offset:5120
	v_lshlrev_b32_e32 v7, 2, v7
	v_and_b32_e32 v7, 32, v7
	v_lshlrev_b32_e32 v22, 10, v22
	v_bitop3_b32 v7, v23, v7, v202 bitop3:0x36
	v_or3_b32 v7, v7, v22, v24
	v_add_co_u32_e32 v20, vcc, s22, v2
	global_store_dwordx4 v7, v[8:11], s[58:59]
	s_waitcnt lgkmcnt(0)
	v_lshlrev_b32_e32 v7, 16, v16
	v_addc_co_u32_e32 v21, vcc, 0, v3, vcc
	v_and_b32_e32 v8, 0xffff0000, v16
	v_lshlrev_b32_e32 v9, 16, v17
	v_and_b32_e32 v10, 0xffff0000, v17
	v_lshlrev_b32_e32 v11, 16, v18
	v_and_b32_e32 v16, 0xffff0000, v18
	v_lshlrev_b32_e32 v17, 16, v19
	v_and_b32_e32 v18, 0xffff0000, v19
	v_add_co_u32_e32 v2, vcc, s23, v2
	s_nop 0
	v_lshlrev_b32_e32 v19, 16, v104
	v_and_b32_e32 v12, 0xffff0000, v104
	v_lshlrev_b32_e32 v22, 16, v105
	v_and_b32_e32 v13, 0xffff0000, v105
	v_lshlrev_b32_e32 v23, 16, v106
	v_and_b32_e32 v14, 0xffff0000, v106
	v_lshlrev_b32_e32 v24, 16, v107
	v_and_b32_e32 v15, 0xffff0000, v107
	v_mul_f32_e32 v8, v12, v8
	v_mul_f32_e32 v9, v22, v9
	v_mul_f32_e32 v10, v13, v10
	v_mul_f32_e32 v11, v23, v11
	v_mul_f32_e32 v12, v14, v16
	v_mul_f32_e32 v13, v24, v17
	v_mul_f32_e32 v14, v15, v18
	v_mul_f32_e32 v7, v19, v7
	v_cvt_pk_bf16_f32 v8, v7, v8
	v_cvt_pk_bf16_f32 v9, v9, v10
	v_cvt_pk_bf16_f32 v10, v11, v12
	v_cvt_pk_bf16_f32 v11, v13, v14
	s_nop 0
	v_add_u32_e32 v7, 20, v6
	v_lshrrev_b32_e32 v16, 2, v7
	v_lshrrev_b32_e32 v17, 3, v7
	v_lshlrev_b32_e32 v18, 6, v7
	v_and_or_b32 v16, v16, s21, v5
	v_and_or_b32 v20, v17, 14, v201
	v_and_b32_e32 v21, 0x3c0, v18
	v_lshlrev_b32_e32 v22, 14, v16
	ds_read_b128 v[16:19], v4 offset:6144
	v_lshlrev_b32_e32 v7, 2, v7
	v_and_b32_e32 v7, 32, v7
	v_lshlrev_b32_e32 v20, 10, v20
	v_bitop3_b32 v7, v21, v7, v202 bitop3:0x36
	v_or3_b32 v7, v7, v20, v22
	global_store_dwordx4 v7, v[8:11], s[58:59]
	s_waitcnt lgkmcnt(0)
	v_lshlrev_b32_e32 v7, 16, v16
	v_addc_co_u32_e32 v3, vcc, 0, v3, vcc
	v_and_b32_e32 v8, 0xffff0000, v16
	v_lshlrev_b32_e32 v9, 16, v17
	v_and_b32_e32 v10, 0xffff0000, v17
	v_lshlrev_b32_e32 v11, 16, v18
	v_and_b32_e32 v16, 0xffff0000, v18
	v_lshlrev_b32_e32 v17, 16, v19
	v_and_b32_e32 v18, 0xffff0000, v19
	s_and_b64 vcc, exec, s[66:67]
	s_nop 0
	v_lshlrev_b32_e32 v19, 16, v108
	v_and_b32_e32 v12, 0xffff0000, v108
	v_lshlrev_b32_e32 v20, 16, v109
	v_and_b32_e32 v13, 0xffff0000, v109
	v_lshlrev_b32_e32 v21, 16, v110
	v_and_b32_e32 v14, 0xffff0000, v110
	v_lshlrev_b32_e32 v22, 16, v111
	v_and_b32_e32 v15, 0xffff0000, v111
	v_mul_f32_e32 v8, v12, v8
	v_mul_f32_e32 v9, v20, v9
	v_mul_f32_e32 v10, v13, v10
	v_mul_f32_e32 v11, v21, v11
	v_mul_f32_e32 v12, v14, v16
	v_mul_f32_e32 v13, v22, v17
	v_mul_f32_e32 v14, v15, v18
	v_mul_f32_e32 v7, v19, v7
	v_cvt_pk_bf16_f32 v8, v7, v8
	v_cvt_pk_bf16_f32 v9, v9, v10
	v_cvt_pk_bf16_f32 v10, v11, v12
	v_cvt_pk_bf16_f32 v11, v13, v14
	s_nop 0
	v_add_u32_e32 v2, 24, v6
	v_add_u32_e32 v3, 28, v6
	v_lshrrev_b32_e32 v6, 2, v2
	v_lshrrev_b32_e32 v7, 3, v2
	v_lshlrev_b32_e32 v16, 6, v2
	v_lshlrev_b32_e32 v2, 2, v2
	v_lshrrev_b32_e32 v17, 2, v3
	v_lshrrev_b32_e32 v18, 3, v3
	v_lshlrev_b32_e32 v19, 6, v3
	v_lshlrev_b32_e32 v3, 2, v3
	v_and_or_b32 v6, v6, s21, v5
	v_and_b32_e32 v16, 0x3c0, v16
	v_and_b32_e32 v2, 32, v2
	v_and_or_b32 v5, v17, s21, v5
	v_and_or_b32 v17, v18, 14, v201
	v_and_b32_e32 v18, 0x3c0, v19
	v_and_b32_e32 v19, 32, v3
	v_bitop3_b32 v16, v16, v2, v202 bitop3:0x36
	v_lshlrev_b32_e32 v20, 14, v5
	ds_read_b128 v[2:5], v4 offset:7168
	v_and_or_b32 v7, v7, 14, v201
	v_lshlrev_b32_e32 v6, 14, v6
	v_lshlrev_b32_e32 v7, 10, v7
	v_lshlrev_b32_e32 v17, 10, v17
	v_bitop3_b32 v18, v18, v19, v202 bitop3:0x36
	v_or3_b32 v6, v16, v7, v6
	v_or3_b32 v7, v18, v17, v20
	global_store_dwordx4 v6, v[8:11], s[58:59]
	s_waitcnt lgkmcnt(0)
	v_lshlrev_b32_e32 v6, 16, v2
	v_and_b32_e32 v2, 0xffff0000, v2
	v_lshlrev_b32_e32 v8, 16, v3
	v_and_b32_e32 v3, 0xffff0000, v3
	v_lshlrev_b32_e32 v9, 16, v4
	v_and_b32_e32 v4, 0xffff0000, v4
	v_lshlrev_b32_e32 v10, 16, v5
	v_and_b32_e32 v5, 0xffff0000, v5
	s_nop 0
	v_lshlrev_b32_e32 v11, 16, v112
	v_and_b32_e32 v12, 0xffff0000, v112
	v_lshlrev_b32_e32 v16, 16, v113
	v_and_b32_e32 v13, 0xffff0000, v113
	v_lshlrev_b32_e32 v17, 16, v114
	v_and_b32_e32 v14, 0xffff0000, v114
	v_lshlrev_b32_e32 v18, 16, v115
	v_and_b32_e32 v15, 0xffff0000, v115
	v_mul_f32_e32 v2, v12, v2
	v_mul_f32_e32 v3, v13, v3
	v_mul_f32_e32 v4, v14, v4
	v_mul_f32_e32 v5, v15, v5
	v_mul_f32_e32 v6, v11, v6
	v_mul_f32_e32 v8, v16, v8
	v_mul_f32_e32 v9, v17, v9
	v_mul_f32_e32 v10, v18, v10
	v_cvt_pk_bf16_f32 v2, v6, v2
	v_cvt_pk_bf16_f32 v3, v8, v3
	v_cvt_pk_bf16_f32 v4, v9, v4
	v_cvt_pk_bf16_f32 v5, v10, v5
	global_store_dwordx4 v7, v[2:5], s[58:59]
	s_waitcnt lgkmcnt(0)
	s_barrier
	s_cbranch_vccnz .LBB0_505

.LBB0_524:
	ds_read_b64_tr_b16 v[190:191], v196 offset:0
	ds_read_b64_tr_b16 v[192:193], v196 offset:0x800
	ds_read_b64_tr_b16 v[232:233], v196 offset:0x1000
	ds_read_b64_tr_b16 v[234:235], v196 offset:0x1800
	ds_read_b64_tr_b16 v[236:237], v196 offset:0x2000
	ds_read_b64_tr_b16 v[238:239], v196 offset:0x2800
	ds_read_b64_tr_b16 v[240:241], v196 offset:0x3000
	ds_read_b64_tr_b16 v[242:243], v196 offset:0x3800
	s_waitcnt lgkmcnt(0)
	s_nop 0
	v_mfma_f32_32x32x16_bf16 v[2:17], v[166:169], v[190:193], v[2:17]
	ds_read_b64_tr_b16 v[190:191], v196 offset:0x200
	ds_read_b64_tr_b16 v[192:193], v196 offset:0xa00
	v_mfma_f32_32x32x16_bf16 v[2:17], v[162:165], v[232:235], v[2:17]
	ds_read_b64_tr_b16 v[232:233], v196 offset:0x1200
	ds_read_b64_tr_b16 v[234:235], v196 offset:0x1a00
	v_mfma_f32_32x32x16_bf16 v[2:17], v[170:173], v[236:239], v[2:17]
	ds_read_b64_tr_b16 v[236:237], v196 offset:0x2200
	ds_read_b64_tr_b16 v[238:239], v196 offset:0x2a00
	ds_read_b64_tr_b16 v[244:245], v196 offset:0x3200
	ds_read_b64_tr_b16 v[246:247], v196 offset:0x3a00
	s_waitcnt lgkmcnt(0)
	v_mfma_f32_32x32x16_bf16 v[2:17], v[174:177], v[240:243], v[2:17]
	v_mfma_f32_32x32x16_bf16 v[50:65], v[166:169], v[190:193], v[50:65]
	ds_read_b64_tr_b16 v[190:191], v196 offset:0x400
	ds_read_b64_tr_b16 v[192:193], v196 offset:0xc00
	v_mfma_f32_32x32x16_bf16 v[50:65], v[162:165], v[232:235], v[50:65]
	ds_read_b64_tr_b16 v[232:233], v196 offset:0x1400
	ds_read_b64_tr_b16 v[234:235], v196 offset:0x1c00
	v_mfma_f32_32x32x16_bf16 v[50:65], v[170:173], v[236:239], v[50:65]
	ds_read_b64_tr_b16 v[236:237], v196 offset:0x2400
	ds_read_b64_tr_b16 v[238:239], v196 offset:0x2c00
	ds_read_b64_tr_b16 v[240:241], v196 offset:0x3400
	ds_read_b64_tr_b16 v[242:243], v196 offset:0x3c00
	s_waitcnt lgkmcnt(0)
	v_mfma_f32_32x32x16_bf16 v[50:65], v[174:177], v[244:247], v[50:65]
	v_mfma_f32_32x32x16_bf16 v[34:49], v[166:169], v[190:193], v[34:49]
	ds_read_b64_tr_b16 v[190:191], v196 offset:0x600
	ds_read_b64_tr_b16 v[192:193], v196 offset:0xe00
	v_mfma_f32_32x32x16_bf16 v[34:49], v[162:165], v[232:235], v[34:49]
	ds_read_b64_tr_b16 v[232:233], v196 offset:0x1600
	ds_read_b64_tr_b16 v[234:235], v196 offset:0x1e00
	v_mfma_f32_32x32x16_bf16 v[34:49], v[170:173], v[236:239], v[34:49]
	ds_read_b64_tr_b16 v[236:237], v196 offset:0x2600
	ds_read_b64_tr_b16 v[238:239], v196 offset:0x2e00
	ds_read_b64_tr_b16 v[244:245], v196 offset:0x3600
	ds_read_b64_tr_b16 v[246:247], v196 offset:0x3e00
	s_waitcnt lgkmcnt(0)
	v_mfma_f32_32x32x16_bf16 v[34:49], v[174:177], v[240:243], v[34:49]
	v_mfma_f32_32x32x16_bf16 v[18:33], v[166:169], v[190:193], v[18:33]
	v_max3_f32 v231, v82, v83, v84
	v_max3_f32 v240, v66, v67, v68
	s_nop 0
	v_max3_f32 v231, v231, v85, v86
	v_max3_f32 v240, v240, v69, v70
	s_barrier
	v_max3_f32 v166, v240, v71, v72
	v_mfma_f32_32x32x16_bf16 v[18:33], v[162:165], v[232:235], v[18:33]
	v_max3_f32 v231, v231, v87, v88
	v_max3_f32 v166, v166, v73, v74
	v_max_f32_e32 v164, v81, v81
	v_max3_f32 v167, v231, v89, v90
	v_max3_f32 v166, v166, v75, v76
	v_max_f32_e32 v165, v97, v97
	v_max3_f32 v167, v167, v91, v92
	v_mfma_f32_32x32x16_bf16 v[18:33], v[170:173], v[236:239], v[18:33]
	v_max3_f32 v167, v167, v93, v94
	v_max3_f32 v166, v166, v77, v78
	v_max_f32_e32 v164, v165, v164
	v_max3_f32 v162, v167, v95, v96
	v_max3_f32 v163, v166, v79, v80
	s_nop 0
	v_max3_f32 v162, v162, v163, v164
	v_mfma_f32_32x32x16_bf16 v[18:33], v[174:177], v[244:247], v[18:33]
	v_mov_b32_e32 v163, v162
	s_nop 1
	v_permlane32_swap_b32_e32 v162, v163
	v_max_f32_e32 v163, v163, v163
	v_max_f32_e32 v162, v162, v162
	v_max_f32_e32 v162, v162, v163
	v_max_f32_e32 v163, v228, v228
	v_max_f32_e32 v163, v163, v162
	v_sub_f32_e32 v164, v162, v228
	v_sub_f32_e32 v162, v228, v163
	v_mul_f32_e32 v162, 0x3e0293ee, v162
	v_exp_f32_e32 v162, v162
	v_cmp_ge_f32_e32 vcc, s16, v164
	s_cmp_eq_u64 vcc, exec
	s_cselect_b64 s[6:7], -1, 0
	s_waitcnt vmcnt(4)
	v_cndmask_b32_e64 v162, v162, 1.0, s[6:7]
	v_cmp_gt_f32_e32 vcc, 1.0, v162
	s_cmp_eq_u64 s[38:39], 0
	s_cbranch_scc1 .Lattn_notlast
	s_waitcnt vmcnt(0)
.Lattn_notlast:
	ds_write_b128 v209, v[146:149] offset:16384
	ds_write_b128 v210, v[150:153] offset:16384
	ds_write_b128 v211, v[154:157] offset:49152
	ds_write_b128 v212, v[158:161] offset:49152
	s_cbranch_vccz .LBB0_528
	s_and_saveexec_b64 s[40:41], s[4:5]
	ds_write_b32 v222, v162 offset:128
	s_or_b64 exec, exec, s[40:41]
	s_waitcnt lgkmcnt(0)
	v_add_u32_e32 v158, s29, v195
	ds_read_b128 v[146:149], v158 offset:224
	ds_read_b128 v[150:153], v158 offset:192
	ds_read_b128 v[154:157], v158 offset:160
	ds_read_b128 v[158:161], v158 offset:128
	s_waitcnt lgkmcnt(3)
	v_pk_mul_f32 v[14:15], v[14:15], v[146:147]
	s_waitcnt lgkmcnt(2)
	v_pk_mul_f32 v[10:11], v[10:11], v[150:151]
	s_waitcnt lgkmcnt(1)
	v_pk_mul_f32 v[6:7], v[6:7], v[154:155]
	v_pk_mul_f32 v[16:17], v[16:17], v[148:149]
	v_pk_mul_f32 v[12:13], v[12:13], v[152:153]
	v_pk_mul_f32 v[8:9], v[8:9], v[156:157]
	s_waitcnt lgkmcnt(0)
	v_pk_mul_f32 v[4:5], v[4:5], v[160:161]
	v_pk_mul_f32 v[2:3], v[2:3], v[158:159]
	v_pk_mul_f32 v[62:63], v[62:63], v[146:147]
	v_pk_mul_f32 v[58:59], v[58:59], v[150:151]
	v_pk_mul_f32 v[54:55], v[54:55], v[154:155]
	v_pk_mul_f32 v[64:65], v[64:65], v[148:149]
	v_pk_mul_f32 v[60:61], v[60:61], v[152:153]
	v_pk_mul_f32 v[56:57], v[56:57], v[156:157]
	v_pk_mul_f32 v[52:53], v[52:53], v[160:161]
	v_pk_mul_f32 v[50:51], v[50:51], v[158:159]
	v_pk_mul_f32 v[46:47], v[46:47], v[146:147]
	v_pk_mul_f32 v[42:43], v[42:43], v[150:151]
	v_pk_mul_f32 v[38:39], v[38:39], v[154:155]
	v_pk_mul_f32 v[48:49], v[48:49], v[148:149]
	v_pk_mul_f32 v[44:45], v[44:45], v[152:153]
	v_pk_mul_f32 v[40:41], v[40:41], v[156:157]
	v_pk_mul_f32 v[36:37], v[36:37], v[160:161]
	v_pk_mul_f32 v[34:35], v[34:35], v[158:159]
	v_pk_mul_f32 v[30:31], v[30:31], v[146:147]
	v_pk_mul_f32 v[26:27], v[26:27], v[150:151]
	v_pk_mul_f32 v[22:23], v[22:23], v[154:155]
	v_pk_mul_f32 v[32:33], v[32:33], v[148:149]
	v_pk_mul_f32 v[28:29], v[28:29], v[152:153]
	v_pk_mul_f32 v[24:25], v[24:25], v[156:157]
	v_pk_mul_f32 v[20:21], v[20:21], v[160:161]
	v_pk_mul_f32 v[18:19], v[18:19], v[158:159]
